# K-loop LDS-DMA SGPR-base form extended to vcc-based sites (35 of 80)
# baseline (speedup 1.0000x reference)
.LBB0_157:
	v_or_b32_e32 v138, 0x10000, v142
	v_add_u32_e32 v139, 0x10400, v142
	ds_read_b128 v[144:147], v138
	ds_read_b128 v[148:151], v139
	v_add_u32_e32 v138, 0x10800, v142
	v_add_u32_e32 v139, 0x10c00, v142
	ds_read_b128 v[152:155], v138
	ds_read_b128 v[156:159], v139
	v_or_b32_e32 v138, 0x14000, v142
	v_add_u32_e32 v139, 0x14400, v142
	ds_read_b128 v[160:163], v138
	ds_read_b128 v[164:167], v139
	v_add_u32_e32 v138, 0x14800, v142
	v_add_u32_e32 v139, 0x14c00, v142
	ds_read_b128 v[168:171], v138
	ds_read_b128 v[172:175], v139
	s_add_u32 s8, vcc_lo, 0xfffc0080
	s_addc_u32 s9, vcc_hi, -1
	s_cmp_eq_u32 s90, 12
	s_cselect_b32 s11, s5, s9
	s_cselect_b32 s10, s92, s8
	s_cselect_b32 s9, s85, s89
	s_cselect_b32 s8, s96, s88
	s_add_i32 m0, s23, 0xc000
	ds_read_b128 v[186:189], v141
	ds_read_b128 v[190:193], v141 offset:1024
	ds_read_b128 v[194:197], v141 offset:2048
	ds_read_b128 v[198:201], v141 offset:3072
	ds_read_b128 v[202:205], v141 offset:4096
	ds_read_b128 v[220:223], v141 offset:5120
	ds_read_b128 v[224:227], v141 offset:6144
	ds_read_b128 v[228:231], v141 offset:7168
	global_load_lds_dwordx4 v134, vcc
	s_add_i32 m0, s23, 0xe000
	s_nop 0
	global_load_lds_dwordx4 v136, vcc
	s_waitcnt vmcnt(8)
	s_waitcnt lgkmcnt(0)
	s_barrier
	s_setprio 1
	s_waitcnt lgkmcnt(0)
	v_mfma_f32_16x16x32_bf16 v[124:127], v[144:147], v[186:189], v[124:127]
	v_mfma_f32_16x16x32_bf16 v[120:123], v[152:155], v[186:189], v[120:123]
	v_mfma_f32_16x16x32_bf16 v[108:111], v[144:147], v[194:197], v[108:111]
	v_mfma_f32_16x16x32_bf16 v[104:107], v[152:155], v[194:197], v[104:107]
	v_mfma_f32_16x16x32_bf16 v[92:95], v[144:147], v[202:205], v[92:95]
	v_mfma_f32_16x16x32_bf16 v[88:91], v[152:155], v[202:205], v[88:91]
	v_mfma_f32_16x16x32_bf16 v[76:79], v[144:147], v[224:227], v[76:79]
	v_mfma_f32_16x16x32_bf16 v[72:75], v[152:155], v[224:227], v[72:75]
	v_mfma_f32_16x16x32_bf16 v[124:127], v[148:151], v[190:193], v[124:127]
	v_mfma_f32_16x16x32_bf16 v[120:123], v[156:159], v[190:193], v[120:123]
	v_mfma_f32_16x16x32_bf16 v[108:111], v[148:151], v[198:201], v[108:111]
	v_mfma_f32_16x16x32_bf16 v[104:107], v[156:159], v[198:201], v[104:107]
	v_mfma_f32_16x16x32_bf16 v[92:95], v[148:151], v[220:223], v[92:95]
	v_mfma_f32_16x16x32_bf16 v[88:91], v[156:159], v[220:223], v[88:91]
	v_mfma_f32_16x16x32_bf16 v[76:79], v[148:151], v[228:231], v[76:79]
	v_mfma_f32_16x16x32_bf16 v[72:75], v[156:159], v[228:231], v[72:75]
	s_setprio 0
	s_setprio 1
	v_mfma_f32_16x16x32_bf16 v[116:119], v[160:163], v[186:189], v[116:119]
	v_mfma_f32_16x16x32_bf16 v[112:115], v[168:171], v[186:189], v[112:115]
	v_mfma_f32_16x16x32_bf16 v[100:103], v[160:163], v[194:197], v[100:103]
	v_mfma_f32_16x16x32_bf16 v[96:99], v[168:171], v[194:197], v[96:99]
	v_mfma_f32_16x16x32_bf16 v[84:87], v[160:163], v[202:205], v[84:87]
	v_mfma_f32_16x16x32_bf16 v[80:83], v[168:171], v[202:205], v[80:83]
	v_mfma_f32_16x16x32_bf16 v[68:71], v[160:163], v[224:227], v[68:71]
	v_mfma_f32_16x16x32_bf16 v[64:67], v[168:171], v[224:227], v[64:67]
	v_mfma_f32_16x16x32_bf16 v[116:119], v[164:167], v[190:193], v[116:119]
	v_mfma_f32_16x16x32_bf16 v[112:115], v[172:175], v[190:193], v[112:115]
	v_mfma_f32_16x16x32_bf16 v[100:103], v[164:167], v[198:201], v[100:103]
	v_mfma_f32_16x16x32_bf16 v[96:99], v[172:175], v[198:201], v[96:99]
	v_mfma_f32_16x16x32_bf16 v[84:87], v[164:167], v[220:223], v[84:87]
	v_mfma_f32_16x16x32_bf16 v[80:83], v[172:175], v[220:223], v[80:83]
	v_mfma_f32_16x16x32_bf16 v[68:71], v[164:167], v[228:231], v[68:71]
	v_mfma_f32_16x16x32_bf16 v[64:67], v[172:175], v[228:231], v[64:67]
	s_setprio 0
	s_barrier
	s_mov_b32 m0, s25
	v_lshl_add_u64 v[138:139], s[8:9], 0, v[176:177]
	s_add_u32 s60, s8, 0x40000
	ds_read_b128 v[186:189], v141 offset:16384
	ds_read_b128 v[190:193], v141 offset:17408
	ds_read_b128 v[194:197], v141 offset:18432
	ds_read_b128 v[198:201], v141 offset:19456
	ds_read_b128 v[202:205], v141 offset:20480
	ds_read_b128 v[220:223], v141 offset:21504
	ds_read_b128 v[224:227], v141 offset:22528
	ds_read_b128 v[228:231], v141 offset:23552
	global_load_lds_dwordx4 v[138:139], off
	v_lshl_add_u64 v[232:233], s[8:9], 0, v[128:129]
	s_mov_b32 m0, s26
	s_addc_u32 s61, s9, 0
	global_load_lds_dwordx4 v[232:233], off
	s_mov_b32 m0, s27
	v_lshl_add_u64 v[236:237], s[10:11], 0, v[130:131]
	global_load_lds_dwordx4 v176, s[60:61]
	s_mov_b32 m0, s28
	s_nop 0
	global_load_lds_dwordx4 v128, s[60:61]
	v_lshl_add_u64 v[234:235], s[10:11], 0, v[132:133]
	s_mov_b32 m0, s23
	s_nop 0
	global_load_lds_dwordx4 v[234:235], off
	s_mov_b32 m0, s29
	s_nop 0
	global_load_lds_dwordx4 v[236:237], off
	s_waitcnt vmcnt(8)
	s_waitcnt lgkmcnt(0)
	s_barrier
	s_setprio 1
	s_waitcnt lgkmcnt(0)
	v_mfma_f32_16x16x32_bf16 v[60:63], v[144:147], v[186:189], v[60:63]
	v_mfma_f32_16x16x32_bf16 v[56:59], v[152:155], v[186:189], v[56:59]
	v_mfma_f32_16x16x32_bf16 v[44:47], v[144:147], v[194:197], v[44:47]
	v_mfma_f32_16x16x32_bf16 v[40:43], v[152:155], v[194:197], v[40:43]
	v_mfma_f32_16x16x32_bf16 v[28:31], v[144:147], v[202:205], v[28:31]
	v_mfma_f32_16x16x32_bf16 v[24:27], v[152:155], v[202:205], v[24:27]
	v_mfma_f32_16x16x32_bf16 v[12:15], v[144:147], v[224:227], v[12:15]
	v_mfma_f32_16x16x32_bf16 v[8:11], v[152:155], v[224:227], v[8:11]
	v_mfma_f32_16x16x32_bf16 v[60:63], v[148:151], v[190:193], v[60:63]
	v_mfma_f32_16x16x32_bf16 v[56:59], v[156:159], v[190:193], v[56:59]
	v_mfma_f32_16x16x32_bf16 v[44:47], v[148:151], v[198:201], v[44:47]
	v_mfma_f32_16x16x32_bf16 v[40:43], v[156:159], v[198:201], v[40:43]
	v_mfma_f32_16x16x32_bf16 v[28:31], v[148:151], v[220:223], v[28:31]
	v_mfma_f32_16x16x32_bf16 v[24:27], v[156:159], v[220:223], v[24:27]
	v_mfma_f32_16x16x32_bf16 v[12:15], v[148:151], v[228:231], v[12:15]
	v_mfma_f32_16x16x32_bf16 v[8:11], v[156:159], v[228:231], v[8:11]
	s_setprio 0
	s_setprio 1
	v_mfma_f32_16x16x32_bf16 v[52:55], v[160:163], v[186:189], v[52:55]
	v_mfma_f32_16x16x32_bf16 v[48:51], v[168:171], v[186:189], v[48:51]
	v_mfma_f32_16x16x32_bf16 v[36:39], v[160:163], v[194:197], v[36:39]
	v_mfma_f32_16x16x32_bf16 v[32:35], v[168:171], v[194:197], v[32:35]
	v_mfma_f32_16x16x32_bf16 v[20:23], v[160:163], v[202:205], v[20:23]
	v_mfma_f32_16x16x32_bf16 v[16:19], v[168:171], v[202:205], v[16:19]
	v_mfma_f32_16x16x32_bf16 v[4:7], v[160:163], v[224:227], v[4:7]
	v_mfma_f32_16x16x32_bf16 v[0:3], v[168:171], v[224:227], v[0:3]
	v_mfma_f32_16x16x32_bf16 v[52:55], v[164:167], v[190:193], v[52:55]
	v_mfma_f32_16x16x32_bf16 v[48:51], v[172:175], v[190:193], v[48:51]
	v_mfma_f32_16x16x32_bf16 v[36:39], v[164:167], v[198:201], v[36:39]
	v_mfma_f32_16x16x32_bf16 v[32:35], v[172:175], v[198:201], v[32:35]
	v_mfma_f32_16x16x32_bf16 v[20:23], v[164:167], v[220:223], v[20:23]
	v_mfma_f32_16x16x32_bf16 v[16:19], v[172:175], v[220:223], v[16:19]
	v_mfma_f32_16x16x32_bf16 v[4:7], v[164:167], v[228:231], v[4:7]
	v_mfma_f32_16x16x32_bf16 v[0:3], v[172:175], v[228:231], v[0:3]
	s_setprio 0
	s_barrier
	v_or_b32_e32 v144, 0x18000, v142
	v_add_u32_e32 v148, 0x18400, v142
	v_add_u32_e32 v152, 0x18800, v142
	v_add_u32_e32 v156, 0x18c00, v142
	v_or_b32_e32 v160, 0x1c000, v142
	v_add_u32_e32 v164, 0x1c400, v142
	v_add_u32_e32 v168, 0x1c800, v142
	v_add_u32_e32 v172, 0x1cc00, v142
	ds_read_b128 v[144:147], v144
	ds_read_b128 v[148:151], v148
	ds_read_b128 v[152:155], v152
	ds_read_b128 v[156:159], v156
	ds_read_b128 v[160:163], v160
	ds_read_b128 v[164:167], v164
	ds_read_b128 v[168:171], v168
	ds_read_b128 v[172:175], v172
	s_add_u32 s10, s10, 0x40000
	s_addc_u32 s11, s11, 0
	s_mov_b32 m0, s30
	ds_read_b128 v[186:189], v141 offset:32768
	ds_read_b128 v[190:193], v141 offset:33792
	ds_read_b128 v[194:197], v141 offset:34816
	ds_read_b128 v[198:201], v141 offset:35840
	ds_read_b128 v[202:205], v141 offset:36864
	ds_read_b128 v[220:223], v141 offset:37888
	ds_read_b128 v[224:227], v141 offset:38912
	ds_read_b128 v[228:231], v141 offset:39936
	global_load_lds_dwordx4 v132, s[10:11]
	v_lshl_add_u64 v[238:239], s[10:11], 0, v[130:131]
	s_mov_b32 m0, s31
	s_nop 0
	global_load_lds_dwordx4 v[238:239], off
	s_waitcnt vmcnt(8)
	s_waitcnt lgkmcnt(0)
	s_barrier
	s_setprio 1
	s_waitcnt lgkmcnt(0)
	v_mfma_f32_16x16x32_bf16 v[124:127], v[144:147], v[186:189], v[124:127]
	v_mfma_f32_16x16x32_bf16 v[120:123], v[152:155], v[186:189], v[120:123]
	v_mfma_f32_16x16x32_bf16 v[108:111], v[144:147], v[194:197], v[108:111]
	v_mfma_f32_16x16x32_bf16 v[104:107], v[152:155], v[194:197], v[104:107]
	v_mfma_f32_16x16x32_bf16 v[92:95], v[144:147], v[202:205], v[92:95]
	v_mfma_f32_16x16x32_bf16 v[88:91], v[152:155], v[202:205], v[88:91]
	v_mfma_f32_16x16x32_bf16 v[76:79], v[144:147], v[224:227], v[76:79]
	v_mfma_f32_16x16x32_bf16 v[72:75], v[152:155], v[224:227], v[72:75]
	v_mfma_f32_16x16x32_bf16 v[124:127], v[148:151], v[190:193], v[124:127]
	v_mfma_f32_16x16x32_bf16 v[120:123], v[156:159], v[190:193], v[120:123]
	v_mfma_f32_16x16x32_bf16 v[108:111], v[148:151], v[198:201], v[108:111]
	v_mfma_f32_16x16x32_bf16 v[104:107], v[156:159], v[198:201], v[104:107]
	v_mfma_f32_16x16x32_bf16 v[92:95], v[148:151], v[220:223], v[92:95]
	v_mfma_f32_16x16x32_bf16 v[88:91], v[156:159], v[220:223], v[88:91]
	v_mfma_f32_16x16x32_bf16 v[76:79], v[148:151], v[228:231], v[76:79]
	v_mfma_f32_16x16x32_bf16 v[72:75], v[156:159], v[228:231], v[72:75]
	s_setprio 0
	s_setprio 1
	v_mfma_f32_16x16x32_bf16 v[116:119], v[160:163], v[186:189], v[116:119]
	v_mfma_f32_16x16x32_bf16 v[112:115], v[168:171], v[186:189], v[112:115]
	v_mfma_f32_16x16x32_bf16 v[100:103], v[160:163], v[194:197], v[100:103]
	v_mfma_f32_16x16x32_bf16 v[96:99], v[168:171], v[194:197], v[96:99]
	v_mfma_f32_16x16x32_bf16 v[84:87], v[160:163], v[202:205], v[84:87]
	v_mfma_f32_16x16x32_bf16 v[80:83], v[168:171], v[202:205], v[80:83]
	v_mfma_f32_16x16x32_bf16 v[68:71], v[160:163], v[224:227], v[68:71]
	v_mfma_f32_16x16x32_bf16 v[64:67], v[168:171], v[224:227], v[64:67]
	v_mfma_f32_16x16x32_bf16 v[116:119], v[164:167], v[190:193], v[116:119]
	v_mfma_f32_16x16x32_bf16 v[112:115], v[172:175], v[190:193], v[112:115]
	v_mfma_f32_16x16x32_bf16 v[100:103], v[164:167], v[198:201], v[100:103]
	v_mfma_f32_16x16x32_bf16 v[96:99], v[172:175], v[198:201], v[96:99]
	v_mfma_f32_16x16x32_bf16 v[84:87], v[164:167], v[220:223], v[84:87]
	v_mfma_f32_16x16x32_bf16 v[80:83], v[172:175], v[220:223], v[80:83]
	v_mfma_f32_16x16x32_bf16 v[68:71], v[164:167], v[228:231], v[68:71]
	v_mfma_f32_16x16x32_bf16 v[64:67], v[172:175], v[228:231], v[64:67]
	s_setprio 0
	s_barrier
	s_mov_b32 m0, s34
	v_lshl_add_u64 v[138:139], v[138:139], 0, s[0:1]
	s_add_u32 s8, s8, 0x40080
	ds_read_b128 v[186:189], v141 offset:49152
	ds_read_b128 v[190:193], v141 offset:50176
	ds_read_b128 v[194:197], v141 offset:51200
	ds_read_b128 v[198:201], v141 offset:52224
	ds_read_b128 v[202:205], v141 offset:53248
	ds_read_b128 v[220:223], v141 offset:54272
	ds_read_b128 v[224:227], v141 offset:55296
	ds_read_b128 v[228:231], v141 offset:56320
	global_load_lds_dwordx4 v[138:139], off
	v_lshl_add_u64 v[138:139], v[232:233], 0, s[0:1]
	s_mov_b32 m0, s35
	s_addc_u32 s9, s9, 0
	global_load_lds_dwordx4 v[138:139], off
	s_mov_b32 m0, s74
	s_nop 0
	global_load_lds_dwordx4 v176, s[8:9]
	s_mov_b32 m0, s75
	s_nop 0
	global_load_lds_dwordx4 v128, s[8:9]
	v_lshl_add_u64 v[138:139], v[234:235], 0, s[0:1]
	s_mov_b32 m0, s42
	s_nop 0
	global_load_lds_dwordx4 v[138:139], off
	v_lshl_add_u64 v[138:139], v[236:237], 0, s[0:1]
	s_mov_b32 m0, s43
	s_nop 0
	global_load_lds_dwordx4 v[138:139], off
	s_waitcnt vmcnt(8)
	s_waitcnt lgkmcnt(0)
	s_barrier
	s_setprio 1
	s_waitcnt lgkmcnt(0)
	v_mfma_f32_16x16x32_bf16 v[60:63], v[144:147], v[186:189], v[60:63]
	v_mfma_f32_16x16x32_bf16 v[56:59], v[152:155], v[186:189], v[56:59]
	v_mfma_f32_16x16x32_bf16 v[44:47], v[144:147], v[194:197], v[44:47]
	v_mfma_f32_16x16x32_bf16 v[40:43], v[152:155], v[194:197], v[40:43]
	v_mfma_f32_16x16x32_bf16 v[28:31], v[144:147], v[202:205], v[28:31]
	v_mfma_f32_16x16x32_bf16 v[24:27], v[152:155], v[202:205], v[24:27]
	v_mfma_f32_16x16x32_bf16 v[12:15], v[144:147], v[224:227], v[12:15]
	v_mfma_f32_16x16x32_bf16 v[8:11], v[152:155], v[224:227], v[8:11]
	v_mfma_f32_16x16x32_bf16 v[60:63], v[148:151], v[190:193], v[60:63]
	v_mfma_f32_16x16x32_bf16 v[56:59], v[156:159], v[190:193], v[56:59]
	v_mfma_f32_16x16x32_bf16 v[44:47], v[148:151], v[198:201], v[44:47]
	v_mfma_f32_16x16x32_bf16 v[40:43], v[156:159], v[198:201], v[40:43]
	v_mfma_f32_16x16x32_bf16 v[28:31], v[148:151], v[220:223], v[28:31]
	v_mfma_f32_16x16x32_bf16 v[24:27], v[156:159], v[220:223], v[24:27]
	v_mfma_f32_16x16x32_bf16 v[12:15], v[148:151], v[228:231], v[12:15]
	v_mfma_f32_16x16x32_bf16 v[8:11], v[156:159], v[228:231], v[8:11]
	s_setprio 0
	s_setprio 1
	v_mfma_f32_16x16x32_bf16 v[52:55], v[160:163], v[186:189], v[52:55]
	v_mfma_f32_16x16x32_bf16 v[48:51], v[168:171], v[186:189], v[48:51]
	v_mfma_f32_16x16x32_bf16 v[36:39], v[160:163], v[194:197], v[36:39]
	v_mfma_f32_16x16x32_bf16 v[32:35], v[168:171], v[194:197], v[32:35]
	v_mfma_f32_16x16x32_bf16 v[20:23], v[160:163], v[202:205], v[20:23]
	v_mfma_f32_16x16x32_bf16 v[16:19], v[168:171], v[202:205], v[16:19]
	v_mfma_f32_16x16x32_bf16 v[4:7], v[160:163], v[224:227], v[4:7]
	v_mfma_f32_16x16x32_bf16 v[0:3], v[168:171], v[224:227], v[0:3]
	v_mfma_f32_16x16x32_bf16 v[52:55], v[164:167], v[190:193], v[52:55]
	v_mfma_f32_16x16x32_bf16 v[48:51], v[172:175], v[190:193], v[48:51]
	v_mfma_f32_16x16x32_bf16 v[36:39], v[164:167], v[198:201], v[36:39]
	v_mfma_f32_16x16x32_bf16 v[32:35], v[172:175], v[198:201], v[32:35]
	v_mfma_f32_16x16x32_bf16 v[20:23], v[164:167], v[220:223], v[20:23]
	v_mfma_f32_16x16x32_bf16 v[16:19], v[172:175], v[220:223], v[16:19]
	v_mfma_f32_16x16x32_bf16 v[4:7], v[164:167], v[228:231], v[4:7]
	v_mfma_f32_16x16x32_bf16 v[0:3], v[172:175], v[228:231], v[0:3]
	s_setprio 0
	s_barrier
	s_add_i32 s90, s90, 2
	s_add_u32 vcc_lo, vcc_lo, 0x100
	s_addc_u32 vcc_hi, vcc_hi, 0
	s_add_u32 s88, s88, 0x100
	s_addc_u32 s89, s89, 0
	s_cmp_gt_u32 s90, 13
	s_cbranch_scc0 .LBB0_157
	s_and_b64 vcc, exec, s[40:41]
	s_cbranch_vccz .LBB0_160
	s_barrier
